# layer-0 out-proj second round (32 context units): vacuous ready poll + acquire removed, base-tile loads of its epilogue staged through LDS-DMA (4 round trips -> 2)
# baseline (speedup 1.0000x reference)
.LBB0_781:
	v_readlane_b32 s24, v253, 17
	v_readlane_b32 s25, v253, 18
	s_andn2_b64 vcc, exec, s[24:25]
	s_cbranch_vccnz .LBB0_1055
	v_readlane_b32 s24, v253, 20
	v_mov_b32_e32 v37, v226
	v_readlane_b32 s25, v253, 21
	s_andn2_b64 vcc, exec, s[24:25]
	v_readfirstlane_b32 s0, v37
	s_cbranch_vccnz .LBB0_786
	s_and_saveexec_b64 s[24:25], s[36:37]
	s_cbranch_execz .LBB0_785
.LBB0_785:
	s_or_b64 exec, exec, s[24:25]
	s_barrier

.LBB0_815:
	s_lshl_b32 s57, s45, 5
	s_sub_i32 s46, s50, 64
	s_and_b64 s[42:43], s[52:53], exec
	s_cselect_b32 s42, s50, s46
	s_ashr_i32 s43, s42, 31
	s_lshl_b64 s[42:43], s[42:43], 20
	s_add_u32 s46, s34, s42
	s_addc_u32 s47, s35, s43
	s_lshl_b32 s34, s44, 8
	s_or_b32 s34, s34, s57
	v_lshrrev_b32_e32 v32, 2, v37
	v_and_or_b32 v184, v32, 12, s34
	s_lshl_b64 s[34:35], s[54:55], 2
	s_add_u32 s52, s56, s34
	v_ashrrev_i32_e32 v185, 31, v184
	s_addc_u32 s53, s51, s35
	v_lshlrev_b64 v[186:187], 2, v[184:185]
	v_ashrrev_i32_e32 v35, 31, v34
	v_or_b32_e32 v200, 16, v34
	v_lshl_add_u64 v[138:139], s[52:53], 0, v[186:187]
	v_lshl_add_u64 v[224:225], s[46:47], 0, v[186:187]
	v_lshlrev_b64 v[208:209], 12, v[34:35]
	v_ashrrev_i32_e32 v201, 31, v200
	flat_load_dwordx4 v[134:137], v[138:139]
	flat_load_dwordx4 v[170:173], v[138:139] offset:64
	flat_load_dwordx4 v[162:165], v[138:139] offset:512
	flat_load_dwordx4 v[154:157], v[138:139] offset:576
	v_lshl_add_u64 v[138:139], v[224:225], 0, v[208:209]
	v_lshlrev_b64 v[204:205], 12, v[200:201]
	flat_load_dwordx4 v[188:191], v[138:139]
	flat_load_dwordx4 v[174:177], v[138:139] offset:64
	flat_load_dwordx4 v[166:169], v[138:139] offset:512
	flat_load_dwordx4 v[158:161], v[138:139] offset:576
	v_lshl_add_u64 v[138:139], v[224:225], 0, v[204:205]
	flat_load_dwordx4 v[150:153], v[138:139]
	flat_load_dwordx4 v[146:149], v[138:139] offset:64
	flat_load_dwordx4 v[142:145], v[138:139] offset:512
	s_nop 0
	flat_load_dwordx4 v[138:141], v[138:139] offset:576
	v_readlane_b32 s98, v254, 58
	s_nop 3
	s_lshl_b32 s98, s98, 14
	v_add_u32_e32 v182, 0x20, v34
	v_lshlrev_b32_e32 v182, 12, v182
	v_mov_b32_e32 v183, 0
	v_lshl_add_u64 v[182:183], v[182:183], 0, v[224:225]
	s_mov_b32 m0, s98
	s_nop 0
	global_load_lds_dwordx4 v[182:183], off
	v_lshl_add_u64 v[182:183], v[182:183], 0, 64
	s_add_i32 m0, s98, 0x400
	s_nop 0
	global_load_lds_dwordx4 v[182:183], off
	v_add_co_u32_e32 v182, vcc, 0x1c0, v182
	s_nop 1
	v_addc_co_u32_e32 v183, vcc, 0, v183, vcc
	s_add_i32 m0, s98, 0x800
	s_nop 0
	global_load_lds_dwordx4 v[182:183], off
	v_lshl_add_u64 v[182:183], v[182:183], 0, 64
	s_add_i32 m0, s98, 0xc00
	s_nop 0
	global_load_lds_dwordx4 v[182:183], off
	v_add_u32_e32 v182, 0x30, v34
	v_lshlrev_b32_e32 v182, 12, v182
	v_mov_b32_e32 v183, 0
	v_lshl_add_u64 v[182:183], v[182:183], 0, v[224:225]
	s_add_i32 m0, s98, 0x1000
	s_nop 0
	global_load_lds_dwordx4 v[182:183], off
	v_lshl_add_u64 v[182:183], v[182:183], 0, 64
	s_add_i32 m0, s98, 0x1400
	s_nop 0
	global_load_lds_dwordx4 v[182:183], off
	v_add_co_u32_e32 v182, vcc, 0x1c0, v182
	s_nop 1
	v_addc_co_u32_e32 v183, vcc, 0, v183, vcc
	s_add_i32 m0, s98, 0x1800
	s_nop 0
	global_load_lds_dwordx4 v[182:183], off
	v_lshl_add_u64 v[182:183], v[182:183], 0, 64
	s_add_i32 m0, s98, 0x1c00
	s_nop 0
	global_load_lds_dwordx4 v[182:183], off
	v_add_u32_e32 v182, 0x80, v34
	v_lshlrev_b32_e32 v182, 12, v182
	v_mov_b32_e32 v183, 0
	v_lshl_add_u64 v[182:183], v[182:183], 0, v[224:225]
	s_add_i32 m0, s98, 0x2000
	s_nop 0
	global_load_lds_dwordx4 v[182:183], off
	v_lshl_add_u64 v[182:183], v[182:183], 0, 64
	s_add_i32 m0, s98, 0x2400
	s_nop 0
	global_load_lds_dwordx4 v[182:183], off
	v_add_co_u32_e32 v182, vcc, 0x1c0, v182
	s_nop 1
	v_addc_co_u32_e32 v183, vcc, 0, v183, vcc
	s_add_i32 m0, s98, 0x2800
	s_nop 0
	global_load_lds_dwordx4 v[182:183], off
	v_lshl_add_u64 v[182:183], v[182:183], 0, 64
	s_add_i32 m0, s98, 0x2c00
	s_nop 0
	global_load_lds_dwordx4 v[182:183], off
	v_add_u32_e32 v182, 0x90, v34
	v_lshlrev_b32_e32 v182, 12, v182
	v_mov_b32_e32 v183, 0
	v_lshl_add_u64 v[182:183], v[182:183], 0, v[224:225]
	s_add_i32 m0, s98, 0x3000
	s_nop 0
	global_load_lds_dwordx4 v[182:183], off
	v_lshl_add_u64 v[182:183], v[182:183], 0, 64
	s_add_i32 m0, s98, 0x3400
	s_nop 0
	global_load_lds_dwordx4 v[182:183], off
	v_add_co_u32_e32 v182, vcc, 0x1c0, v182
	s_nop 1
	v_addc_co_u32_e32 v183, vcc, 0, v183, vcc
	s_add_i32 m0, s98, 0x3800
	s_nop 0
	global_load_lds_dwordx4 v[182:183], off
	v_lshl_add_u64 v[182:183], v[182:183], 0, 64
	s_add_i32 m0, s98, 0x3c00
	s_nop 0
	global_load_lds_dwordx4 v[182:183], off
	v_readlane_b32 s52, v254, 36
	s_add_u32 s24, s24, s42
	s_mov_b32 s46, s1
	s_mov_b32 s47, s49
	v_readlane_b32 s53, v254, 37
	s_mov_b32 s52, s1
	s_addc_u32 s25, s25, s43
	s_cmp_eq_u64 s[46:47], s[52:53]
	s_mov_b32 s43, s53
	v_lshl_add_u64 v[210:211], s[24:25], 0, v[186:187]
	s_cselect_b64 s[54:55], -1, 0
	v_writelane_b32 v254, s42, 36
	s_cmp_lg_u64 s[46:47], s[52:53]
	v_lshl_add_u64 v[186:187], v[210:211], 0, v[208:209]
	v_writelane_b32 v254, s43, 37
	s_cselect_b64 s[46:47], -1, 0
	s_and_b64 vcc, exec, s[54:55]
	s_waitcnt vmcnt(16) lgkmcnt(0)
	v_pk_mul_f32 v[220:221], s[48:49], v[136:137] op_sel_hi:[0,1]
	v_pk_mul_f32 v[214:215], s[48:49], v[134:135] op_sel_hi:[0,1]
	v_pk_fma_f32 v[136:137], v[132:133], v[220:221], v[190:191]
	v_pk_fma_f32 v[134:135], v[130:131], v[214:215], v[188:189]
	s_cbranch_vccz .LBB0_817
	flat_store_dwordx4 v[186:187], v[134:137]

.LBB0_857:
	v_pk_fma_f32 v[2:3], v[2:3], v[166:167], v[140:141]
	v_pk_fma_f32 v[0:1], v[0:1], v[168:169], v[138:139]
	s_mov_b64 s[42:43], -1
	s_and_b64 vcc, exec, s[46:47]
	s_cbranch_vccz .LBB0_1053
	s_barrier
	v_and_b32_e32 v58, 64, v229
	v_xor_b32_e32 v32, 16, v229
	v_add_u32_e32 v59, 64, v58
	v_cmp_lt_i32_e32 vcc, v32, v59
	v_mul_f32_e32 v60, v137, v137
	v_fmac_f32_e32 v60, v136, v136
	v_cndmask_b32_e32 v32, v229, v32, vcc
	v_lshlrev_b32_e32 v58, 2, v32
	v_mul_f32_e32 v32, v135, v135
	v_fmac_f32_e32 v32, v134, v134
	v_add_f32_e32 v32, v32, v60
	v_mul_f32_e32 v60, v131, v131
	v_mul_f32_e32 v61, v133, v133
	v_fmac_f32_e32 v60, v130, v130
	v_fmac_f32_e32 v61, v132, v132
	v_add_f32_e32 v60, v60, v61
	v_add_f32_e32 v32, v32, v60
	v_mul_f32_e32 v60, v127, v127
	v_mul_f32_e32 v61, v129, v129
	v_fmac_f32_e32 v60, v126, v126
	v_fmac_f32_e32 v61, v128, v128
	v_add_f32_e32 v60, v60, v61
	v_add_f32_e32 v32, v32, v60
	v_mul_f32_e32 v60, v123, v123
	v_mul_f32_e32 v61, v125, v125
	v_fmac_f32_e32 v60, v122, v122
	v_fmac_f32_e32 v61, v124, v124
	v_add_f32_e32 v60, v60, v61
	v_add_f32_e32 v32, v32, v60
	ds_bpermute_b32 v60, v58, v32
	v_xor_b32_e32 v61, 32, v229
	v_cmp_lt_i32_e32 vcc, v61, v59
	s_lshl_b32 s42, s45, 2
	s_add_i32 s45, s42, 0
	v_cndmask_b32_e32 v59, v229, v61, vcc
	v_lshlrev_b32_e32 v59, 2, v59
	s_waitcnt lgkmcnt(0)
	v_add_f32_e32 v60, v32, v60
	ds_bpermute_b32 v61, v59, v60
	v_and_b32_e32 v32, 63, v37
	v_cmp_gt_u32_e32 vcc, 16, v32
	s_and_saveexec_b64 s[42:43], vcc
	s_cbranch_execz .LBB0_860
	s_lshl_b32 s46, s41, 10
	s_add_i32 s46, s45, s46
	s_waitcnt lgkmcnt(0)
	v_add_f32_e32 v60, v60, v61
	v_lshl_add_u32 v61, v178, 4, s46
	ds_write_b32 v61, v60
